# grid barrier: acquire-side L1 invalidate (buffer_inv sc1) issued at arrival (before spinning; leader: together with wbl2) instead of after release; stacks on epilogue+bias rewrites
# speedup vs baseline: 1.0173x; 1.0100x over previous
; __device__ __forceinline__ unsigned xb_ld(unsigned* p)              { return __hip_atomic_load(p, __ATOMIC_RELAXED, __HIP_MEMORY_SCOPE_AGENT); }
; __device__ __forceinline__ unsigned xb_add(unsigned* p, unsigned v) { return __hip_atomic_fetch_add(p, v, __ATOMIC_RELAXED, __HIP_MEMORY_SCOPE_AGENT); }
; #define XB_SPIN(cond, bar) do { unsigned _sp = 0; while (cond) { __builtin_amdgcn_s_sleep(1); \
;     if ((++_sp & 255u) == 0u) { if (xb_ld(&(bar)[XB_TMO])) break; if (_sp > XB_SPIN_CAP) { atomicAdd(&(bar)[XB_TMO], 1u); break; } } } } while (0)
; __device__ __forceinline__ void xcd_barrier(const XcdBarrier& b) {
;     asm volatile("s_waitcnt vmcnt(0)" ::: "memory");
;     __syncthreads();
;     if (threadIdx.x == 0) {
;         unsigned* bar = b.bar;
;         __builtin_amdgcn_s_waitcnt(0);
;         unsigned nloc = b.st[0], nx = b.st[1];
;         if (nloc == 0u) { xcd_barrier_complete(bar, b.x, nloc, nx); b.st[0] = nloc; b.st[1] = nx; }
;         const unsigned old = xb_add(&bar[XB_XSUB(b.x)], 1u);
;         const unsigned gen = old / nloc;
;         if (old + 1u == (gen + 1u) * nloc) {
;             __builtin_amdgcn_fence(__ATOMIC_RELEASE, "agent");
;             asm volatile("s_waitcnt vmcnt(0)" ::: "memory");
;             const unsigned og = xb_add(&bar[XB_TOP], 1u);
;             const unsigned tg = og / nx;
;             if (og + 1u == (tg + 1u) * nx) xb_add(&bar[XB_TOPGEN], 1u);
;             else XB_SPIN(xb_ld(&bar[XB_TOPGEN]) == tg, bar);
;             __builtin_amdgcn_fence(__ATOMIC_ACQUIRE, "agent");
;             xb_add(&bar[XB_XGEN(b.x)], 1u);
;             asm volatile("s_waitcnt vmcnt(0)" ::: "memory");
;         } else {
;             XB_SPIN(xb_ld(&bar[XB_XGEN(b.x)]) == gen, bar);
.LBB0_97:
	s_or_b64 exec, exec, s[6:7]
	v_cvt_f32_u32_e32 v4, v2
	s_waitcnt vmcnt(0)
	v_readfirstlane_b32 s4, v3
	v_sub_u32_e32 v3, 0, v2
	v_rcp_iflag_f32_e32 v4, v4
	v_add_u32_e32 v5, s4, v1
	v_mul_f32_e32 v4, 0x4f7ffffe, v4
	v_cvt_u32_f32_e32 v4, v4
	v_mul_lo_u32 v1, v3, v4
	v_mul_hi_u32 v1, v4, v1
	v_add_u32_e32 v1, v4, v1
	v_mul_hi_u32 v1, v5, v1
	v_mul_lo_u32 v3, v1, v2
	v_sub_u32_e32 v3, v5, v3
	v_add_u32_e32 v4, 1, v1
	v_cmp_ge_u32_e32 vcc, v3, v2
	s_nop 1
	v_cndmask_b32_e32 v1, v1, v4, vcc
	v_sub_u32_e32 v4, v3, v2
	v_cndmask_b32_e32 v3, v3, v4, vcc
	v_add_u32_e32 v4, 1, v1
	v_cmp_ge_u32_e32 vcc, v3, v2
	v_add_u32_e32 v3, 1, v5
	s_nop 0
	v_cndmask_b32_e32 v1, v1, v4, vcc
	v_mul_lo_u32 v4, v2, v1
	v_add_u32_e32 v2, v4, v2
	v_cmp_ne_u32_e32 vcc, v3, v2
	s_and_saveexec_b64 s[4:5], vcc
	s_xor_b64 s[4:5], exec, s[4:5]
	s_cbranch_execz .LBB0_111
	buffer_inv sc1
	s_waitcnt lgkmcnt(0)
	v_mov_b32_e32 v0, 0x2000
	global_load_dword v0, v0, s[2:3] offset:1024 sc1
	s_add_u32 s12, s2, 0x2400
	s_addc_u32 s13, s3, 0
	s_waitcnt vmcnt(0)
	v_cmp_eq_u32_e32 vcc, v0, v1
	s_and_saveexec_b64 s[6:7], vcc
	s_cbranch_execz .LBB0_110
	s_add_u32 s8, s60, 0x80200
	s_addc_u32 s9, s61, 0
	s_mov_b32 s26, 1
	s_mov_b64 s[16:17], 0
	v_mov_b32_e32 v0, 0
	s_branch .LBB0_101

; __device__ __forceinline__ unsigned xb_ld(unsigned* p)              { return __hip_atomic_load(p, __ATOMIC_RELAXED, __HIP_MEMORY_SCOPE_AGENT); }
; __device__ __forceinline__ unsigned xb_add(unsigned* p, unsigned v) { return __hip_atomic_fetch_add(p, v, __ATOMIC_RELAXED, __HIP_MEMORY_SCOPE_AGENT); }
; #define XB_SPIN(cond, bar) do { unsigned _sp = 0; while (cond) { __builtin_amdgcn_s_sleep(1); \
;     if ((++_sp & 255u) == 0u) { if (xb_ld(&(bar)[XB_TMO])) break; if (_sp > XB_SPIN_CAP) { atomicAdd(&(bar)[XB_TMO], 1u); break; } } } } while (0)
; __device__ __forceinline__ void xcd_barrier(const XcdBarrier& b) {
;     ...
;         if (old + 1u == (gen + 1u) * nloc) {
;             __builtin_amdgcn_fence(__ATOMIC_RELEASE, "agent");
;             asm volatile("s_waitcnt vmcnt(0)" ::: "memory");
;             const unsigned og = xb_add(&bar[XB_TOP], 1u);
;             const unsigned tg = og / nx;
;             if (og + 1u == (tg + 1u) * nx) xb_add(&bar[XB_TOPGEN], 1u);
;             else XB_SPIN(xb_ld(&bar[XB_TOPGEN]) == tg, bar);
;             __builtin_amdgcn_fence(__ATOMIC_ACQUIRE, "agent");
;             xb_add(&bar[XB_XGEN(b.x)], 1u);
;             asm volatile("s_waitcnt vmcnt(0)" ::: "memory");
;         } else {
;             XB_SPIN(xb_ld(&bar[XB_XGEN(b.x)]) == gen, bar);
;             __builtin_amdgcn_fence(__ATOMIC_ACQUIRE, "agent");
;             asm volatile("s_waitcnt vmcnt(0)" ::: "memory");
.LBB0_110:
	s_or_b64 exec, exec, s[6:7]
	s_waitcnt vmcnt(0)
	s_waitcnt vmcnt(0)
.LBB0_111:
	s_andn2_saveexec_b64 s[4:5], s[4:5]
	s_cbranch_execz .LBB0_131
	s_mov_b64 s[4:5], exec
	buffer_wbl2 sc1
	buffer_inv sc1
	s_waitcnt lgkmcnt(0)
	s_waitcnt vmcnt(0)
	v_mbcnt_lo_u32_b32 v1, s4, 0
	v_mbcnt_hi_u32_b32 v1, s5, v1
	v_cmp_eq_u32_e32 vcc, 0, v1
	s_and_saveexec_b64 s[6:7], vcc
	s_cbranch_execz .LBB0_114
	s_bcnt1_i32_b64 s4, s[4:5]
	v_mov_b32_e32 v2, 0x83000
	v_mov_b32_e32 v3, s4
	global_atomic_add v2, v2, v3, s[60:61] offset:1024 sc0

; __device__ __forceinline__ unsigned xb_ld(unsigned* p)              { return __hip_atomic_load(p, __ATOMIC_RELAXED, __HIP_MEMORY_SCOPE_AGENT); }
; __device__ __forceinline__ unsigned xb_add(unsigned* p, unsigned v) { return __hip_atomic_fetch_add(p, v, __ATOMIC_RELAXED, __HIP_MEMORY_SCOPE_AGENT); }
; #define XB_SPIN(cond, bar) do { unsigned _sp = 0; while (cond) { __builtin_amdgcn_s_sleep(1); \
;     if ((++_sp & 255u) == 0u) { if (xb_ld(&(bar)[XB_TMO])) break; if (_sp > XB_SPIN_CAP) { atomicAdd(&(bar)[XB_TMO], 1u); break; } } } } while (0)
; __device__ __forceinline__ void xcd_barrier(const XcdBarrier& b) {
;     ...
;             else XB_SPIN(xb_ld(&bar[XB_TOPGEN]) == tg, bar);
;             __builtin_amdgcn_fence(__ATOMIC_ACQUIRE, "agent");
;             xb_add(&bar[XB_XGEN(b.x)], 1u);
.LBB0_128:
	s_or_b64 exec, exec, s[4:5]
	s_mov_b64 s[4:5], exec
	v_mbcnt_lo_u32_b32 v0, s4, 0
	v_mbcnt_hi_u32_b32 v0, s5, v0
	v_cmp_eq_u32_e32 vcc, 0, v0
	s_waitcnt vmcnt(0)
	s_and_saveexec_b64 s[6:7], vcc
	s_cbranch_execz .LBB0_130
	s_bcnt1_i32_b64 s4, s[4:5]
	v_mov_b32_e32 v0, 0x2000
	v_mov_b32_e32 v1, s4
	global_atomic_add v0, v1, s[2:3] offset:1024

; __device__ __forceinline__ unsigned xb_ld(unsigned* p)              { return __hip_atomic_load(p, __ATOMIC_RELAXED, __HIP_MEMORY_SCOPE_AGENT); }
; __device__ __forceinline__ unsigned xb_add(unsigned* p, unsigned v) { return __hip_atomic_fetch_add(p, v, __ATOMIC_RELAXED, __HIP_MEMORY_SCOPE_AGENT); }
; #define XB_SPIN(cond, bar) do { unsigned _sp = 0; while (cond) { __builtin_amdgcn_s_sleep(1); \
;     if ((++_sp & 255u) == 0u) { if (xb_ld(&(bar)[XB_TMO])) break; if (_sp > XB_SPIN_CAP) { atomicAdd(&(bar)[XB_TMO], 1u); break; } } } } while (0)
; __device__ __forceinline__ void xcd_barrier(const XcdBarrier& b) {
;     ...
;         const unsigned old = xb_add(&bar[XB_XSUB(b.x)], 1u);
;         const unsigned gen = old / nloc;
;         if (old + 1u == (gen + 1u) * nloc) {
;             __builtin_amdgcn_fence(__ATOMIC_RELEASE, "agent");
;             asm volatile("s_waitcnt vmcnt(0)" ::: "memory");
;             const unsigned og = xb_add(&bar[XB_TOP], 1u);
;             const unsigned tg = og / nx;
;             if (og + 1u == (tg + 1u) * nx) xb_add(&bar[XB_TOPGEN], 1u);
;             else XB_SPIN(xb_ld(&bar[XB_TOPGEN]) == tg, bar);
;             __builtin_amdgcn_fence(__ATOMIC_ACQUIRE, "agent");
;             xb_add(&bar[XB_XGEN(b.x)], 1u);
;             asm volatile("s_waitcnt vmcnt(0)" ::: "memory");
;         } else {
;             XB_SPIN(xb_ld(&bar[XB_XGEN(b.x)]) == gen, bar);
.LBB0_356:
	s_or_b64 exec, exec, s[6:7]
	v_cvt_f32_u32_e32 v4, v2
	s_waitcnt vmcnt(0)
	v_readfirstlane_b32 s4, v3
	v_sub_u32_e32 v3, 0, v2
	v_rcp_iflag_f32_e32 v4, v4
	v_add_u32_e32 v5, s4, v1
	v_mul_f32_e32 v4, 0x4f7ffffe, v4
	v_cvt_u32_f32_e32 v4, v4
	v_mul_lo_u32 v1, v3, v4
	v_mul_hi_u32 v1, v4, v1
	v_add_u32_e32 v1, v4, v1
	v_mul_hi_u32 v1, v5, v1
	v_mul_lo_u32 v3, v1, v2
	v_sub_u32_e32 v3, v5, v3
	v_add_u32_e32 v4, 1, v1
	v_cmp_ge_u32_e32 vcc, v3, v2
	s_nop 1
	v_cndmask_b32_e32 v1, v1, v4, vcc
	v_sub_u32_e32 v4, v3, v2
	v_cndmask_b32_e32 v3, v3, v4, vcc
	v_add_u32_e32 v4, 1, v1
	v_cmp_ge_u32_e32 vcc, v3, v2
	v_add_u32_e32 v3, 1, v5
	s_nop 0
	v_cndmask_b32_e32 v1, v1, v4, vcc
	v_mul_lo_u32 v4, v2, v1
	v_add_u32_e32 v2, v4, v2
	v_cmp_ne_u32_e32 vcc, v3, v2
	s_and_saveexec_b64 s[4:5], vcc
	s_xor_b64 s[4:5], exec, s[4:5]
	s_cbranch_execz .LBB0_370
	buffer_inv sc1
	s_waitcnt lgkmcnt(0)
	v_mov_b32_e32 v0, 0x2000
	global_load_dword v0, v0, s[2:3] offset:1024 sc1
	s_add_u32 s10, s2, 0x2400
	s_addc_u32 s11, s3, 0
	s_waitcnt vmcnt(0)
	v_cmp_eq_u32_e32 vcc, v0, v1
	s_and_saveexec_b64 s[6:7], vcc
	s_cbranch_execz .LBB0_369
	s_add_u32 s8, s60, 0x80200
	s_addc_u32 s9, s61, 0
	s_mov_b32 s24, 1
	s_mov_b64 s[12:13], 0
	v_mov_b32_e32 v0, 0
	s_branch .LBB0_360

; __device__ __forceinline__ unsigned xb_ld(unsigned* p)              { return __hip_atomic_load(p, __ATOMIC_RELAXED, __HIP_MEMORY_SCOPE_AGENT); }
; __device__ __forceinline__ unsigned xb_add(unsigned* p, unsigned v) { return __hip_atomic_fetch_add(p, v, __ATOMIC_RELAXED, __HIP_MEMORY_SCOPE_AGENT); }
; #define XB_SPIN(cond, bar) do { unsigned _sp = 0; while (cond) { __builtin_amdgcn_s_sleep(1); \
;     if ((++_sp & 255u) == 0u) { if (xb_ld(&(bar)[XB_TMO])) break; if (_sp > XB_SPIN_CAP) { atomicAdd(&(bar)[XB_TMO], 1u); break; } } } } while (0)
; __device__ __forceinline__ void xcd_barrier(const XcdBarrier& b) {
;     ...
;         const unsigned old = xb_add(&bar[XB_XSUB(b.x)], 1u);
;         const unsigned gen = old / nloc;
;         if (old + 1u == (gen + 1u) * nloc) {
;             __builtin_amdgcn_fence(__ATOMIC_RELEASE, "agent");
;             asm volatile("s_waitcnt vmcnt(0)" ::: "memory");
;             const unsigned og = xb_add(&bar[XB_TOP], 1u);
;             const unsigned tg = og / nx;
;             if (og + 1u == (tg + 1u) * nx) xb_add(&bar[XB_TOPGEN], 1u);
;             else XB_SPIN(xb_ld(&bar[XB_TOPGEN]) == tg, bar);
;             __builtin_amdgcn_fence(__ATOMIC_ACQUIRE, "agent");
;             xb_add(&bar[XB_XGEN(b.x)], 1u);
;             asm volatile("s_waitcnt vmcnt(0)" ::: "memory");
;         } else {
;             XB_SPIN(xb_ld(&bar[XB_XGEN(b.x)]) == gen, bar);
.LBB0_437:
	s_or_b64 exec, exec, s[6:7]
	v_cvt_f32_u32_e32 v4, v2
	s_waitcnt vmcnt(0)
	v_readfirstlane_b32 s4, v3
	v_sub_u32_e32 v3, 0, v2
	v_rcp_iflag_f32_e32 v4, v4
	v_add_u32_e32 v5, s4, v1
	v_mul_f32_e32 v4, 0x4f7ffffe, v4
	v_cvt_u32_f32_e32 v4, v4
	v_mul_lo_u32 v1, v3, v4
	v_mul_hi_u32 v1, v4, v1
	v_add_u32_e32 v1, v4, v1
	v_mul_hi_u32 v1, v5, v1
	v_mul_lo_u32 v3, v1, v2
	v_sub_u32_e32 v3, v5, v3
	v_add_u32_e32 v4, 1, v1
	v_cmp_ge_u32_e32 vcc, v3, v2
	s_nop 1
	v_cndmask_b32_e32 v1, v1, v4, vcc
	v_sub_u32_e32 v4, v3, v2
	v_cndmask_b32_e32 v3, v3, v4, vcc
	v_add_u32_e32 v4, 1, v1
	v_cmp_ge_u32_e32 vcc, v3, v2
	v_add_u32_e32 v3, 1, v5
	s_nop 0
	v_cndmask_b32_e32 v1, v1, v4, vcc
	v_mul_lo_u32 v4, v2, v1
	v_add_u32_e32 v2, v4, v2
	v_cmp_ne_u32_e32 vcc, v3, v2
	s_and_saveexec_b64 s[4:5], vcc
	s_xor_b64 s[4:5], exec, s[4:5]
	s_cbranch_execz .LBB0_451
	buffer_inv sc1
	s_waitcnt lgkmcnt(0)
	v_mov_b32_e32 v0, 0x2000
	global_load_dword v0, v0, s[2:3] offset:1024 sc1
	s_add_u32 s10, s2, 0x2400
	s_addc_u32 s11, s3, 0
	s_waitcnt vmcnt(0)
	v_cmp_eq_u32_e32 vcc, v0, v1
	s_and_saveexec_b64 s[6:7], vcc
	s_cbranch_execz .LBB0_450
	s_add_u32 s8, s48, 0x80200
	s_addc_u32 s9, s49, 0
	s_mov_b32 s22, 1
	s_mov_b64 s[12:13], 0
	v_mov_b32_e32 v0, 0
	s_branch .LBB0_441

; __device__ __forceinline__ unsigned xb_add(unsigned* p, unsigned v) { return __hip_atomic_fetch_add(p, v, __ATOMIC_RELAXED, __HIP_MEMORY_SCOPE_AGENT); }
; __device__ __forceinline__ void xcd_barrier(const XcdBarrier& b) {
;     ...
;         if (old + 1u == (gen + 1u) * nloc) {
;             __builtin_amdgcn_fence(__ATOMIC_RELEASE, "agent");
;             asm volatile("s_waitcnt vmcnt(0)" ::: "memory");
;             const unsigned og = xb_add(&bar[XB_TOP], 1u);
;             const unsigned tg = og / nx;
;             if (og + 1u == (tg + 1u) * nx) xb_add(&bar[XB_TOPGEN], 1u);
.LBB0_451:
	s_andn2_saveexec_b64 s[4:5], s[4:5]
	s_cbranch_execz .LBB0_471
	s_mov_b64 s[4:5], exec
	buffer_wbl2 sc1
	buffer_inv sc1
	s_waitcnt lgkmcnt(0)
	s_waitcnt vmcnt(0)
	v_mbcnt_lo_u32_b32 v1, s4, 0
	v_mbcnt_hi_u32_b32 v1, s5, v1
	v_cmp_eq_u32_e32 vcc, 0, v1
	s_and_saveexec_b64 s[6:7], vcc
	s_cbranch_execz .LBB0_454
	s_bcnt1_i32_b64 s4, s[4:5]
	v_mov_b32_e32 v2, 0x83000
	v_mov_b32_e32 v3, s4
	global_atomic_add v2, v2, v3, s[48:49] offset:1024 sc0

; __device__ __forceinline__ unsigned xb_ld(unsigned* p)              { return __hip_atomic_load(p, __ATOMIC_RELAXED, __HIP_MEMORY_SCOPE_AGENT); }
; __device__ __forceinline__ unsigned xb_add(unsigned* p, unsigned v) { return __hip_atomic_fetch_add(p, v, __ATOMIC_RELAXED, __HIP_MEMORY_SCOPE_AGENT); }
; #define XB_SPIN(cond, bar) do { unsigned _sp = 0; while (cond) { __builtin_amdgcn_s_sleep(1); \
;     if ((++_sp & 255u) == 0u) { if (xb_ld(&(bar)[XB_TMO])) break; if (_sp > XB_SPIN_CAP) { atomicAdd(&(bar)[XB_TMO], 1u); break; } } } } while (0)
; __device__ __forceinline__ void xcd_barrier(const XcdBarrier& b) {
;     ...
;         const unsigned old = xb_add(&bar[XB_XSUB(b.x)], 1u);
;         const unsigned gen = old / nloc;
;         if (old + 1u == (gen + 1u) * nloc) {
;             __builtin_amdgcn_fence(__ATOMIC_RELEASE, "agent");
;             asm volatile("s_waitcnt vmcnt(0)" ::: "memory");
;             const unsigned og = xb_add(&bar[XB_TOP], 1u);
;             const unsigned tg = og / nx;
;             if (og + 1u == (tg + 1u) * nx) xb_add(&bar[XB_TOPGEN], 1u);
;             else XB_SPIN(xb_ld(&bar[XB_TOPGEN]) == tg, bar);
;             __builtin_amdgcn_fence(__ATOMIC_ACQUIRE, "agent");
;             xb_add(&bar[XB_XGEN(b.x)], 1u);
;             asm volatile("s_waitcnt vmcnt(0)" ::: "memory");
;         } else {
;             XB_SPIN(xb_ld(&bar[XB_XGEN(b.x)]) == gen, bar);
.LBB0_519:
	s_or_b64 exec, exec, s[6:7]
	v_cvt_f32_u32_e32 v4, v2
	s_waitcnt vmcnt(0)
	v_readfirstlane_b32 s4, v3
	v_sub_u32_e32 v3, 0, v2
	v_rcp_iflag_f32_e32 v4, v4
	v_add_u32_e32 v5, s4, v1
	v_mul_f32_e32 v4, 0x4f7ffffe, v4
	v_cvt_u32_f32_e32 v4, v4
	v_mul_lo_u32 v1, v3, v4
	v_mul_hi_u32 v1, v4, v1
	v_add_u32_e32 v1, v4, v1
	v_mul_hi_u32 v1, v5, v1
	v_mul_lo_u32 v3, v1, v2
	v_sub_u32_e32 v3, v5, v3
	v_add_u32_e32 v4, 1, v1
	v_cmp_ge_u32_e32 vcc, v3, v2
	s_nop 1
	v_cndmask_b32_e32 v1, v1, v4, vcc
	v_sub_u32_e32 v4, v3, v2
	v_cndmask_b32_e32 v3, v3, v4, vcc
	v_add_u32_e32 v4, 1, v1
	v_cmp_ge_u32_e32 vcc, v3, v2
	v_add_u32_e32 v3, 1, v5
	s_nop 0
	v_cndmask_b32_e32 v1, v1, v4, vcc
	v_mul_lo_u32 v4, v2, v1
	v_add_u32_e32 v2, v4, v2
	v_cmp_ne_u32_e32 vcc, v3, v2
	s_and_saveexec_b64 s[4:5], vcc
	s_xor_b64 s[4:5], exec, s[4:5]
	s_cbranch_execz .LBB0_533
	buffer_inv sc1
	s_waitcnt lgkmcnt(0)
	v_mov_b32_e32 v0, 0x2000
	global_load_dword v0, v0, s[2:3] offset:1024 sc1
	s_add_u32 s10, s2, 0x2400
	s_addc_u32 s11, s3, 0
	s_waitcnt vmcnt(0)
	v_cmp_eq_u32_e32 vcc, v0, v1
	s_and_saveexec_b64 s[6:7], vcc
	s_cbranch_execz .LBB0_532
	s_add_u32 s8, s68, 0x80200
	s_addc_u32 s9, s69, 0
	s_mov_b32 s22, 1
	s_mov_b64 s[12:13], 0
	v_mov_b32_e32 v0, 0
	s_branch .LBB0_523

; __device__ __forceinline__ unsigned xb_add(unsigned* p, unsigned v) { return __hip_atomic_fetch_add(p, v, __ATOMIC_RELAXED, __HIP_MEMORY_SCOPE_AGENT); }
; __device__ __forceinline__ void xcd_barrier(const XcdBarrier& b) {
;     ...
;         if (old + 1u == (gen + 1u) * nloc) {
;             __builtin_amdgcn_fence(__ATOMIC_RELEASE, "agent");
;             asm volatile("s_waitcnt vmcnt(0)" ::: "memory");
;             const unsigned og = xb_add(&bar[XB_TOP], 1u);
;             const unsigned tg = og / nx;
;             if (og + 1u == (tg + 1u) * nx) xb_add(&bar[XB_TOPGEN], 1u);
.LBB0_533:
	s_andn2_saveexec_b64 s[4:5], s[4:5]
	s_cbranch_execz .LBB0_553
	s_mov_b64 s[4:5], exec
	buffer_wbl2 sc1
	buffer_inv sc1
	s_waitcnt lgkmcnt(0)
	s_waitcnt vmcnt(0)
	v_mbcnt_lo_u32_b32 v1, s4, 0
	v_mbcnt_hi_u32_b32 v1, s5, v1
	v_cmp_eq_u32_e32 vcc, 0, v1
	s_and_saveexec_b64 s[6:7], vcc
	s_cbranch_execz .LBB0_536
	s_bcnt1_i32_b64 s4, s[4:5]
	v_mov_b32_e32 v2, 0x83000
	v_mov_b32_e32 v3, s4
	global_atomic_add v2, v2, v3, s[68:69] offset:1024 sc0

; __device__ __forceinline__ unsigned xb_ld(unsigned* p)              { return __hip_atomic_load(p, __ATOMIC_RELAXED, __HIP_MEMORY_SCOPE_AGENT); }
; __device__ __forceinline__ unsigned xb_add(unsigned* p, unsigned v) { return __hip_atomic_fetch_add(p, v, __ATOMIC_RELAXED, __HIP_MEMORY_SCOPE_AGENT); }
; #define XB_SPIN(cond, bar) do { unsigned _sp = 0; while (cond) { __builtin_amdgcn_s_sleep(1); \
;     if ((++_sp & 255u) == 0u) { if (xb_ld(&(bar)[XB_TMO])) break; if (_sp > XB_SPIN_CAP) { atomicAdd(&(bar)[XB_TMO], 1u); break; } } } } while (0)
; __device__ __forceinline__ void xcd_barrier(const XcdBarrier& b) {
;     ...
;         const unsigned old = xb_add(&bar[XB_XSUB(b.x)], 1u);
;         const unsigned gen = old / nloc;
;         if (old + 1u == (gen + 1u) * nloc) {
;             __builtin_amdgcn_fence(__ATOMIC_RELEASE, "agent");
;             asm volatile("s_waitcnt vmcnt(0)" ::: "memory");
;             const unsigned og = xb_add(&bar[XB_TOP], 1u);
;             const unsigned tg = og / nx;
;             if (og + 1u == (tg + 1u) * nx) xb_add(&bar[XB_TOPGEN], 1u);
;             else XB_SPIN(xb_ld(&bar[XB_TOPGEN]) == tg, bar);
;             __builtin_amdgcn_fence(__ATOMIC_ACQUIRE, "agent");
;             xb_add(&bar[XB_XGEN(b.x)], 1u);
;             asm volatile("s_waitcnt vmcnt(0)" ::: "memory");
;         } else {
;             XB_SPIN(xb_ld(&bar[XB_XGEN(b.x)]) == gen, bar);
.LBB0_629:
	s_or_b64 exec, exec, s[8:9]
	v_cvt_f32_u32_e32 v4, v2
	s_waitcnt vmcnt(0)
	v_readfirstlane_b32 s6, v3
	v_sub_u32_e32 v3, 0, v2
	v_rcp_iflag_f32_e32 v4, v4
	v_add_u32_e32 v5, s6, v1
	v_mul_f32_e32 v4, 0x4f7ffffe, v4
	v_cvt_u32_f32_e32 v4, v4
	v_mul_lo_u32 v1, v3, v4
	v_mul_hi_u32 v1, v4, v1
	v_add_u32_e32 v1, v4, v1
	v_mul_hi_u32 v1, v5, v1
	v_mul_lo_u32 v3, v1, v2
	v_sub_u32_e32 v3, v5, v3
	v_add_u32_e32 v4, 1, v1
	v_cmp_ge_u32_e32 vcc, v3, v2
	s_nop 1
	v_cndmask_b32_e32 v1, v1, v4, vcc
	v_sub_u32_e32 v4, v3, v2
	v_cndmask_b32_e32 v3, v3, v4, vcc
	v_add_u32_e32 v4, 1, v1
	v_cmp_ge_u32_e32 vcc, v3, v2
	v_add_u32_e32 v3, 1, v5
	s_nop 0
	v_cndmask_b32_e32 v1, v1, v4, vcc
	v_mul_lo_u32 v4, v2, v1
	v_add_u32_e32 v2, v4, v2
	v_cmp_ne_u32_e32 vcc, v3, v2
	s_and_saveexec_b64 s[6:7], vcc
	s_xor_b64 s[6:7], exec, s[6:7]
	s_cbranch_execz .LBB0_643
	buffer_inv sc1
	s_waitcnt lgkmcnt(0)
	v_mov_b32_e32 v0, 0x2000
	global_load_dword v0, v0, s[4:5] offset:1024 sc1
	s_add_u32 s12, s4, 0x2400
	s_addc_u32 s13, s5, 0
	s_waitcnt vmcnt(0)
	v_cmp_eq_u32_e32 vcc, v0, v1
	s_and_saveexec_b64 s[8:9], vcc
	s_cbranch_execz .LBB0_642
	s_add_u32 s10, s68, 0x80200
	s_addc_u32 s11, s69, 0
	s_mov_b32 s24, 1
	s_mov_b64 s[14:15], 0
	v_mov_b32_e32 v0, 0
	s_branch .LBB0_633

; __device__ __forceinline__ unsigned xb_ld(unsigned* p)              { return __hip_atomic_load(p, __ATOMIC_RELAXED, __HIP_MEMORY_SCOPE_AGENT); }
; __device__ __forceinline__ unsigned xb_add(unsigned* p, unsigned v) { return __hip_atomic_fetch_add(p, v, __ATOMIC_RELAXED, __HIP_MEMORY_SCOPE_AGENT); }
; #define XB_SPIN(cond, bar) do { unsigned _sp = 0; while (cond) { __builtin_amdgcn_s_sleep(1); \
;     if ((++_sp & 255u) == 0u) { if (xb_ld(&(bar)[XB_TMO])) break; if (_sp > XB_SPIN_CAP) { atomicAdd(&(bar)[XB_TMO], 1u); break; } } } } while (0)
; __device__ __forceinline__ void xcd_barrier(const XcdBarrier& b) {
;     ...
;         if (old + 1u == (gen + 1u) * nloc) {
;             __builtin_amdgcn_fence(__ATOMIC_RELEASE, "agent");
;             asm volatile("s_waitcnt vmcnt(0)" ::: "memory");
;             const unsigned og = xb_add(&bar[XB_TOP], 1u);
;             const unsigned tg = og / nx;
;             if (og + 1u == (tg + 1u) * nx) xb_add(&bar[XB_TOPGEN], 1u);
;             else XB_SPIN(xb_ld(&bar[XB_TOPGEN]) == tg, bar);
;             __builtin_amdgcn_fence(__ATOMIC_ACQUIRE, "agent");
;             xb_add(&bar[XB_XGEN(b.x)], 1u);
;             asm volatile("s_waitcnt vmcnt(0)" ::: "memory");
;         } else {
;             XB_SPIN(xb_ld(&bar[XB_XGEN(b.x)]) == gen, bar);
;             __builtin_amdgcn_fence(__ATOMIC_ACQUIRE, "agent");
;             asm volatile("s_waitcnt vmcnt(0)" ::: "memory");
.LBB0_642:
	s_or_b64 exec, exec, s[8:9]
	s_waitcnt vmcnt(0)
	s_waitcnt vmcnt(0)
.LBB0_643:
	s_andn2_saveexec_b64 s[6:7], s[6:7]
	s_cbranch_execz .LBB0_663
	s_mov_b64 s[6:7], exec
	buffer_wbl2 sc1
	buffer_inv sc1
	s_waitcnt lgkmcnt(0)
	s_waitcnt vmcnt(0)
	v_mbcnt_lo_u32_b32 v1, s6, 0
	v_mbcnt_hi_u32_b32 v1, s7, v1
	v_cmp_eq_u32_e32 vcc, 0, v1
	s_and_saveexec_b64 s[8:9], vcc
	s_cbranch_execz .LBB0_646
	s_bcnt1_i32_b64 s6, s[6:7]
	v_mov_b32_e32 v2, 0x83000
	v_mov_b32_e32 v3, s6
	global_atomic_add v2, v2, v3, s[68:69] offset:1024 sc0

; __device__ __forceinline__ unsigned xb_ld(unsigned* p)              { return __hip_atomic_load(p, __ATOMIC_RELAXED, __HIP_MEMORY_SCOPE_AGENT); }
; __device__ __forceinline__ unsigned xb_add(unsigned* p, unsigned v) { return __hip_atomic_fetch_add(p, v, __ATOMIC_RELAXED, __HIP_MEMORY_SCOPE_AGENT); }
; #define XB_SPIN(cond, bar) do { unsigned _sp = 0; while (cond) { __builtin_amdgcn_s_sleep(1); \
;     if ((++_sp & 255u) == 0u) { if (xb_ld(&(bar)[XB_TMO])) break; if (_sp > XB_SPIN_CAP) { atomicAdd(&(bar)[XB_TMO], 1u); break; } } } } while (0)
; __device__ __forceinline__ void xcd_barrier(const XcdBarrier& b) {
;     ...
;             else XB_SPIN(xb_ld(&bar[XB_TOPGEN]) == tg, bar);
;             __builtin_amdgcn_fence(__ATOMIC_ACQUIRE, "agent");
;             xb_add(&bar[XB_XGEN(b.x)], 1u);
.LBB0_660:
	s_or_b64 exec, exec, s[6:7]
	s_mov_b64 s[6:7], exec
	v_mbcnt_lo_u32_b32 v0, s6, 0
	v_mbcnt_hi_u32_b32 v0, s7, v0
	v_cmp_eq_u32_e32 vcc, 0, v0
	s_waitcnt vmcnt(0)
	s_and_saveexec_b64 s[8:9], vcc
	s_cbranch_execz .LBB0_662
	s_bcnt1_i32_b64 s6, s[6:7]
	v_mov_b32_e32 v0, 0x2000
	v_mov_b32_e32 v1, s6
	global_atomic_add v0, v1, s[4:5] offset:1024

; __device__ __forceinline__ unsigned xb_ld(unsigned* p)              { return __hip_atomic_load(p, __ATOMIC_RELAXED, __HIP_MEMORY_SCOPE_AGENT); }
; __device__ __forceinline__ unsigned xb_add(unsigned* p, unsigned v) { return __hip_atomic_fetch_add(p, v, __ATOMIC_RELAXED, __HIP_MEMORY_SCOPE_AGENT); }
; #define XB_SPIN(cond, bar) do { unsigned _sp = 0; while (cond) { __builtin_amdgcn_s_sleep(1); \
;     if ((++_sp & 255u) == 0u) { if (xb_ld(&(bar)[XB_TMO])) break; if (_sp > XB_SPIN_CAP) { atomicAdd(&(bar)[XB_TMO], 1u); break; } } } } while (0)
; __device__ __forceinline__ void xcd_barrier(const XcdBarrier& b) {
;     ...
;         const unsigned old = xb_add(&bar[XB_XSUB(b.x)], 1u);
;         const unsigned gen = old / nloc;
;         if (old + 1u == (gen + 1u) * nloc) {
;             __builtin_amdgcn_fence(__ATOMIC_RELEASE, "agent");
;             asm volatile("s_waitcnt vmcnt(0)" ::: "memory");
;             const unsigned og = xb_add(&bar[XB_TOP], 1u);
;             const unsigned tg = og / nx;
;             if (og + 1u == (tg + 1u) * nx) xb_add(&bar[XB_TOPGEN], 1u);
;             else XB_SPIN(xb_ld(&bar[XB_TOPGEN]) == tg, bar);
;             __builtin_amdgcn_fence(__ATOMIC_ACQUIRE, "agent");
;             xb_add(&bar[XB_XGEN(b.x)], 1u);
;             asm volatile("s_waitcnt vmcnt(0)" ::: "memory");
;         } else {
;             XB_SPIN(xb_ld(&bar[XB_XGEN(b.x)]) == gen, bar);
.LBB0_935:
	s_or_b64 exec, exec, s[10:11]
	v_cvt_f32_u32_e32 v4, v2
	s_waitcnt vmcnt(0)
	v_readfirstlane_b32 s6, v3
	v_sub_u32_e32 v3, 0, v2
	v_rcp_iflag_f32_e32 v4, v4
	v_add_u32_e32 v5, s6, v1
	v_mul_f32_e32 v4, 0x4f7ffffe, v4
	v_cvt_u32_f32_e32 v4, v4
	v_mul_lo_u32 v1, v3, v4
	v_mul_hi_u32 v1, v4, v1
	v_add_u32_e32 v1, v4, v1
	v_mul_hi_u32 v1, v5, v1
	v_mul_lo_u32 v3, v1, v2
	v_sub_u32_e32 v3, v5, v3
	v_add_u32_e32 v4, 1, v1
	v_cmp_ge_u32_e32 vcc, v3, v2
	s_nop 1
	v_cndmask_b32_e32 v1, v1, v4, vcc
	v_sub_u32_e32 v4, v3, v2
	v_cndmask_b32_e32 v3, v3, v4, vcc
	v_add_u32_e32 v4, 1, v1
	v_cmp_ge_u32_e32 vcc, v3, v2
	v_add_u32_e32 v3, 1, v5
	s_nop 0
	v_cndmask_b32_e32 v1, v1, v4, vcc
	v_mul_lo_u32 v4, v2, v1
	v_add_u32_e32 v2, v4, v2
	v_cmp_ne_u32_e32 vcc, v3, v2
	s_and_saveexec_b64 s[6:7], vcc
	s_xor_b64 s[6:7], exec, s[6:7]
	s_cbranch_execz .LBB0_949
	buffer_inv sc1
	s_waitcnt lgkmcnt(0)
	v_mov_b32_e32 v0, 0x2000
	global_load_dword v0, v0, s[4:5] offset:1024 sc1
	s_add_u32 s14, s4, 0x2400
	s_addc_u32 s15, s5, 0
	s_waitcnt vmcnt(0)
	v_cmp_eq_u32_e32 vcc, v0, v1
	s_and_saveexec_b64 s[10:11], vcc
	s_cbranch_execz .LBB0_948
	s_add_u32 s12, s68, 0x80200
	s_addc_u32 s13, s69, 0
	s_mov_b32 s26, 1
	s_mov_b64 s[16:17], 0
	v_mov_b32_e32 v0, 0
	s_branch .LBB0_939

; __device__ __forceinline__ unsigned xb_ld(unsigned* p)              { return __hip_atomic_load(p, __ATOMIC_RELAXED, __HIP_MEMORY_SCOPE_AGENT); }
; __device__ __forceinline__ unsigned xb_add(unsigned* p, unsigned v) { return __hip_atomic_fetch_add(p, v, __ATOMIC_RELAXED, __HIP_MEMORY_SCOPE_AGENT); }
; #define XB_SPIN(cond, bar) do { unsigned _sp = 0; while (cond) { __builtin_amdgcn_s_sleep(1); \
;     if ((++_sp & 255u) == 0u) { if (xb_ld(&(bar)[XB_TMO])) break; if (_sp > XB_SPIN_CAP) { atomicAdd(&(bar)[XB_TMO], 1u); break; } } } } while (0)
; __device__ __forceinline__ void xcd_barrier(const XcdBarrier& b) {
;     ...
;         if (old + 1u == (gen + 1u) * nloc) {
;             __builtin_amdgcn_fence(__ATOMIC_RELEASE, "agent");
;             asm volatile("s_waitcnt vmcnt(0)" ::: "memory");
;             const unsigned og = xb_add(&bar[XB_TOP], 1u);
;             const unsigned tg = og / nx;
;             if (og + 1u == (tg + 1u) * nx) xb_add(&bar[XB_TOPGEN], 1u);
;             else XB_SPIN(xb_ld(&bar[XB_TOPGEN]) == tg, bar);
;             __builtin_amdgcn_fence(__ATOMIC_ACQUIRE, "agent");
;             xb_add(&bar[XB_XGEN(b.x)], 1u);
;             asm volatile("s_waitcnt vmcnt(0)" ::: "memory");
;         } else {
;             XB_SPIN(xb_ld(&bar[XB_XGEN(b.x)]) == gen, bar);
;             __builtin_amdgcn_fence(__ATOMIC_ACQUIRE, "agent");
;             asm volatile("s_waitcnt vmcnt(0)" ::: "memory");
.LBB0_948:
	s_or_b64 exec, exec, s[10:11]
	s_waitcnt vmcnt(0)
	s_waitcnt vmcnt(0)
.LBB0_949:
	s_andn2_saveexec_b64 s[6:7], s[6:7]
	s_cbranch_execz .LBB0_969
	s_mov_b64 s[6:7], exec
	buffer_wbl2 sc1
	buffer_inv sc1
	s_waitcnt lgkmcnt(0)
	s_waitcnt vmcnt(0)
	v_mbcnt_lo_u32_b32 v1, s6, 0
	v_mbcnt_hi_u32_b32 v1, s7, v1
	v_cmp_eq_u32_e32 vcc, 0, v1
	s_and_saveexec_b64 s[10:11], vcc
	s_cbranch_execz .LBB0_952
	s_bcnt1_i32_b64 s6, s[6:7]
	v_mov_b32_e32 v2, 0x83000
	v_mov_b32_e32 v3, s6
	global_atomic_add v2, v2, v3, s[68:69] offset:1024 sc0

; __device__ __forceinline__ unsigned xb_ld(unsigned* p)              { return __hip_atomic_load(p, __ATOMIC_RELAXED, __HIP_MEMORY_SCOPE_AGENT); }
; __device__ __forceinline__ unsigned xb_add(unsigned* p, unsigned v) { return __hip_atomic_fetch_add(p, v, __ATOMIC_RELAXED, __HIP_MEMORY_SCOPE_AGENT); }
; #define XB_SPIN(cond, bar) do { unsigned _sp = 0; while (cond) { __builtin_amdgcn_s_sleep(1); \
;     if ((++_sp & 255u) == 0u) { if (xb_ld(&(bar)[XB_TMO])) break; if (_sp > XB_SPIN_CAP) { atomicAdd(&(bar)[XB_TMO], 1u); break; } } } } while (0)
; __device__ __forceinline__ void xcd_barrier(const XcdBarrier& b) {
;     ...
;             else XB_SPIN(xb_ld(&bar[XB_TOPGEN]) == tg, bar);
;             __builtin_amdgcn_fence(__ATOMIC_ACQUIRE, "agent");
;             xb_add(&bar[XB_XGEN(b.x)], 1u);
.LBB0_966:
	s_or_b64 exec, exec, s[6:7]
	s_mov_b64 s[6:7], exec
	v_mbcnt_lo_u32_b32 v0, s6, 0
	v_mbcnt_hi_u32_b32 v0, s7, v0
	v_cmp_eq_u32_e32 vcc, 0, v0
	s_waitcnt vmcnt(0)
	s_and_saveexec_b64 s[10:11], vcc
	s_cbranch_execz .LBB0_968
	s_bcnt1_i32_b64 s6, s[6:7]
	v_mov_b32_e32 v0, 0x2000
	v_mov_b32_e32 v1, s6
	global_atomic_add v0, v1, s[4:5] offset:1024
